# attention: Q-fragment and sink loads of both sub-blocks hoisted above the K/V staging
# speedup vs baseline: 1.0110x; 1.0110x over previous
.LBB0_208:
	v_cvt_f32_ubyte0_e32 v0, s93
	v_rcp_iflag_f32_e32 v2, v0
	s_mov_b32 s16, 0x45000000
	s_bfe_u32 s63, s61, 0x20004
	s_mul_hi_i32 s61, s60, 0xc00
	v_mul_f32_e32 v2, 0x45000000, v2
	v_trunc_f32_e32 v2, v2
	v_cvt_u32_f32_e32 v3, v2
	v_fma_f32 v2, -v2, v0, s16
	v_cmp_ge_f32_e64 s[16:17], |v2|, v0
	s_cmp_lg_u64 s[16:17], 0
	v_readfirstlane_b32 s16, v3
	s_addc_u32 s16, s16, 0
	s_lshl_b32 s72, s1, 7
	s_and_b32 s73, s16, 0xffff
	s_mul_i32 s1, s60, 0xc00
	v_readlane_b32 s16, v251, 9
	v_readlane_b32 s17, v251, 10
	s_add_u32 s16, s16, s1
	s_addc_u32 s17, s17, s61
	s_sub_i32 s64, s72, s23
	s_ashr_i32 s1, s0, 31
	v_add_u32_e32 v3, s64, v114
	s_lshl_b64 s[0:1], s[0:1], 11
	v_cmp_lt_i32_e32 vcc, -1, v3
	s_or_b64 s[58:59], s[0:1], s[58:59]
	s_and_b64 s[0:1], s[4:5], vcc
	v_cmp_gt_i32_e32 vcc, s73, v3
	s_lshl_b32 s61, s63, 6
	s_and_b64 s[66:67], s[0:1], vcc
	s_lshl_b32 s100, s63, 2
	s_add_i32 s100, s100, s18
	s_andn2_b64 vcc, exec, s[52:53]
	s_cbranch_vccnz .Lattn_nosink
	v_mov_b32_e32 v161, s100
	v_lshlrev_b32_e32 v161, 2, v161
	global_load_dword v160, v161, s[2:3]
.Lattn_nosink:
	s_lshl_b32 s100, s100, 7
	s_add_u32 s100, s16, s100
	s_addc_u32 s101, s17, 0
	v_mov_b32_e32 v162, v90
	v_mov_b32_e32 v163, 0
	v_lshl_add_u64 v[162:163], s[100:101], 0, v[162:163]
	s_or_b32 s100, s72, s90
	v_or_b32_e32 v164, s100, v87
	v_mov_b64_e32 v[166:167], s[58:59]
	v_mad_u64_u32 v[164:165], vcc, v164, s93, v[166:167]
	v_mov_b32_e32 v169, 0
	v_mad_u64_u32 v[166:167], vcc, v164, s19, 0
	v_mov_b32_e32 v168, v167
	v_mad_u64_u32 v[168:169], vcc, v165, s19, v[168:169]
	v_mov_b32_e32 v167, v168
	v_lshl_add_u64 v[166:167], v[166:167], 1, v[162:163]
	global_load_dwordx4 v[64:67], v[166:167], off
	global_load_dwordx4 v[68:71], v[166:167], off offset:32
	global_load_dwordx4 v[72:75], v[166:167], off offset:64
	global_load_dwordx4 v[76:79], v[166:167], off offset:96
	s_or_b32 s100, s72, s91
	v_or_b32_e32 v164, s100, v87
	v_mov_b64_e32 v[170:171], s[58:59]
	v_mad_u64_u32 v[164:165], vcc, v164, s93, v[170:171]
	v_mov_b32_e32 v173, 0
	v_mad_u64_u32 v[170:171], vcc, v164, s19, 0
	v_mov_b32_e32 v172, v171
	v_mad_u64_u32 v[172:173], vcc, v165, s19, v[172:173]
	v_mov_b32_e32 v171, v172
	v_lshl_add_u64 v[170:171], v[170:171], 1, v[162:163]
	global_load_dwordx4 v[176:179], v[170:171], off
	global_load_dwordx4 v[180:183], v[170:171], off offset:32
	global_load_dwordx4 v[184:187], v[170:171], off offset:64
	global_load_dwordx4 v[188:191], v[170:171], off offset:96
	v_mov_b32_e32 v2, 0
	v_lshlrev_b32_e32 v0, 1, v84
	v_mov_b32_e32 v6, 0
	v_mov_b32_e32 v7, 0
	v_mov_b32_e32 v8, 0
	v_mov_b32_e32 v9, 0
	v_mov_b32_e32 v10, 0
	v_mov_b32_e32 v11, 0
	v_mov_b32_e32 v12, 0
	v_mov_b32_e32 v13, 0
	s_barrier
	s_and_saveexec_b64 s[0:1], s[66:67]
	s_cbranch_execz .LBB0_210
	v_mov_b64_e32 v[4:5], s[58:59]
	v_mad_u64_u32 v[4:5], s[66:67], v3, s93, v[4:5]
	v_mad_u64_u32 v[6:7], s[66:67], v4, s19, 0
	v_mov_b32_e32 v4, v7
	v_mad_u64_u32 v[4:5], s[66:67], v5, s19, v[4:5]
	v_mov_b32_e32 v7, v4
	v_lshl_add_u64 v[4:5], v[6:7], 1, s[16:17]
	s_lshl_b32 s80, s61, 1
	v_lshl_add_u64 v[4:5], v[4:5], 0, s[80:81]
	v_lshl_add_u64 v[4:5], v[4:5], 0, v[0:1]
	global_load_dwordx4 v[6:9], v[4:5], off offset:2048
	global_load_dwordx4 v[10:13], v[4:5], off offset:2560

.LBB0_239:
	s_or_b64 exec, exec, s[62:63]
	s_add_i32 s0, s98, s18
	s_lshl_b32 s62, s0, 6
	s_ashr_i32 s63, s62, 31
	s_lshl_b64 s[64:65], s[62:63], 1
	s_add_u32 s16, s16, s64
	s_addc_u32 s17, s17, s65
	s_ashr_i32 s1, s0, 31
	s_lshl_b64 s[0:1], s[0:1], 2
	s_add_u32 s62, s2, s0
	s_addc_u32 s63, s3, s1
	s_or_b32 s66, s72, s90
	v_mov_b32_e32 v91, v1
	v_or_b32_e32 v0, s66, v87
	s_waitcnt vmcnt(0)
	v_mov_b64_e32 v[2:3], s[58:59]
	v_lshl_add_u64 v[98:99], s[16:17], 0, v[90:91]
	v_mad_u64_u32 v[94:95], s[16:17], v0, s93, v[2:3]
	v_mad_u64_u32 v[2:3], s[16:17], v94, s19, 0
	v_mov_b32_e32 v0, v3
	v_mad_u64_u32 v[4:5], s[16:17], v95, s19, v[0:1]
	v_mov_b32_e32 v3, v4
	v_lshl_add_u64 v[2:3], v[2:3], 1, v[98:99]
	s_waitcnt lgkmcnt(0)
	s_barrier
	v_cndmask_b32_e64 v0, 0, 1, s[52:53]
	v_cmp_ne_u32_e64 s[16:17], 1, v0
	s_andn2_b64 vcc, exec, s[52:53]
	s_cbranch_vccnz .LBB0_241
	v_mov_b32_e32 v138, v89
	v_mul_f32_e32 v93, 0x3fb8aa3b, v160
	s_branch .LBB0_242

.LBB0_252:
	s_or_b64 exec, exec, s[60:61]
	s_or_b32 s60, s72, s91
	v_or_b32_e32 v0, s60, v87
	v_mov_b64_e32 v[2:3], s[58:59]
	v_mad_u64_u32 v[94:95], s[58:59], v0, s93, v[2:3]
	v_mad_u64_u32 v[2:3], s[58:59], v94, s19, 0
	v_mov_b32_e32 v0, v3
	v_mad_u64_u32 v[4:5], s[58:59], v95, s19, v[0:1]
	v_mov_b32_e32 v3, v4
	v_mov_b64_e32 v[64:65], v[176:177]
	v_mov_b64_e32 v[66:67], v[178:179]
	v_mov_b64_e32 v[68:69], v[180:181]
	v_mov_b64_e32 v[70:71], v[182:183]
	v_mov_b64_e32 v[72:73], v[184:185]
	v_mov_b64_e32 v[74:75], v[186:187]
	v_mov_b64_e32 v[76:77], v[188:189]
	v_mov_b64_e32 v[78:79], v[190:191]
	s_and_b64 vcc, exec, s[16:17]
	s_cbranch_vccnz .LBB0_254
	v_mov_b32_e32 v93, v89
	v_mul_f32_e32 v138, 0x3fb8aa3b, v160
	s_branch .LBB0_255

.LBB0_255:
	s_sub_i32 s16, s60, s23
	s_sub_i32 s17, 0, s16
	s_ashr_i32 s17, s17, 5
	s_sub_i32 s58, s66, s16
	s_ashr_i32 s16, s16, 31
	s_ashr_i32 s59, s58, 5
	s_and_b32 s58, s16, s17
	v_lshl_add_u32 v0, s58, 5, v121
	v_mad_u64_u32 v[10:11], s[16:17], v0, s77, v[86:87]
	ds_read_b128 v[2:5], v10
	ds_read_b128 v[6:9], v10 offset:32
	s_waitcnt lgkmcnt(1)
	v_mfma_f32_32x32x16_bf16 v[48:63], v[2:5], v[64:67], 0
	ds_read_b128 v[2:5], v10 offset:64
	s_min_i32 s16, s83, s59
	v_mov_b32_e32 v31, 0
	s_cmp_gt_i32 s58, s16
	s_waitcnt lgkmcnt(1)
	v_mfma_f32_32x32x16_bf16 v[48:63], v[6:9], v[68:71], v[48:63]
	s_waitcnt lgkmcnt(0)
	v_mfma_f32_32x32x16_bf16 v[48:63], v[2:5], v[72:75], v[48:63]
	ds_read_b128 v[2:5], v10 offset:96
	s_waitcnt lgkmcnt(0)
	v_mfma_f32_32x32x16_bf16 v[48:63], v[2:5], v[76:79], v[48:63]
	s_cbranch_scc1 .LBB0_262
	v_mov_b32_e32 v14, v1
	v_mov_b32_e32 v15, v1
	s_mul_i32 s59, s58, 0x1800
	v_mov_b32_e32 v0, v1
	v_mov_b32_e32 v2, v1
	v_mov_b32_e32 v3, v1
	v_mov_b32_e32 v4, v1
	v_mov_b32_e32 v5, v1
	v_mov_b32_e32 v6, v1
	v_mov_b32_e32 v7, v1
	v_mov_b32_e32 v8, v1
	v_mov_b32_e32 v9, v1
	v_mov_b32_e32 v10, v1
	v_mov_b32_e32 v11, v1
	v_mov_b32_e32 v12, v1
	v_mov_b32_e32 v13, v1
	v_mov_b64_e32 v[30:31], v[14:15]
	v_mov_b64_e32 v[46:47], v[14:15]
	v_readlane_b32 s98, v248, 2
	s_add_i32 s17, s58, -1
	v_add_u32_e32 v112, s59, v125
	v_lshl_add_u32 v113, s58, 7, v124
	v_mov_b64_e32 v[28:29], v[12:13]
	v_mov_b64_e32 v[26:27], v[10:11]
	v_mov_b64_e32 v[24:25], v[8:9]
	v_mov_b64_e32 v[22:23], v[6:7]
	v_mov_b64_e32 v[20:21], v[4:5]
	v_mov_b64_e32 v[18:19], v[2:3]
	v_mov_b64_e32 v[16:17], v[0:1]
	v_mov_b64_e32 v[44:45], v[12:13]
	v_mov_b64_e32 v[42:43], v[10:11]
	v_mov_b64_e32 v[40:41], v[8:9]
	v_mov_b64_e32 v[38:39], v[6:7]
	v_mov_b64_e32 v[36:37], v[4:5]
	v_mov_b64_e32 v[34:35], v[2:3]
	v_mov_b64_e32 v[32:33], v[0:1]
	v_readlane_b32 s99, v248, 3
	v_readlane_b32 s60, v248, 31
	v_readlane_b32 s61, v248, 32

	.amdhsa_kernel _Z4mega6Paramsii
		.amdhsa_group_segment_fixed_size 0
		.amdhsa_private_segment_fixed_size 0
		.amdhsa_kernarg_size 432
		.amdhsa_user_sgpr_count 2
		.amdhsa_user_sgpr_dispatch_ptr 0
		.amdhsa_user_sgpr_queue_ptr 0
		.amdhsa_user_sgpr_kernarg_segment_ptr 1
		.amdhsa_user_sgpr_dispatch_id 0
		.amdhsa_user_sgpr_kernarg_preload_length 0
		.amdhsa_user_sgpr_kernarg_preload_offset 0
		.amdhsa_user_sgpr_private_segment_size 0
		.amdhsa_uses_dynamic_stack 0
		.amdhsa_enable_private_segment 0
		.amdhsa_system_sgpr_workgroup_id_x 1
		.amdhsa_system_sgpr_workgroup_id_y 0
		.amdhsa_system_sgpr_workgroup_id_z 0
		.amdhsa_system_sgpr_workgroup_info 0
		.amdhsa_system_vgpr_workitem_id 2
		.amdhsa_next_free_vgpr 252
		.amdhsa_next_free_sgpr 102
		.amdhsa_accum_offset 252
		.amdhsa_reserve_vcc 1
		.amdhsa_float_round_mode_32 0
		.amdhsa_float_round_mode_16_64 0
		.amdhsa_float_denorm_mode_32 3
		.amdhsa_float_denorm_mode_16_64 3
		.amdhsa_dx10_clamp 1
		.amdhsa_ieee_mode 1
		.amdhsa_fp16_overflow 0
		.amdhsa_tg_split 0
		.amdhsa_exception_fp_ieee_invalid_op 0
		.amdhsa_exception_fp_denorm_src 0
		.amdhsa_exception_fp_ieee_div_zero 0
		.amdhsa_exception_fp_ieee_overflow 0
		.amdhsa_exception_fp_ieee_underflow 0
		.amdhsa_exception_fp_ieee_inexact 0
		.amdhsa_exception_int_div_zero 0
	.end_amdhsa_kernel

amdhsa.kernels:
  - .agpr_count:     0
    .args:
      - .offset:         0
        .size:           168
        .value_kind:     by_value
      - .offset:         168
        .size:           4
        .value_kind:     by_value
      - .offset:         172
        .size:           4
        .value_kind:     by_value
      - .offset:         176
        .size:           4
        .value_kind:     hidden_block_count_x
      - .offset:         180
        .size:           4
        .value_kind:     hidden_block_count_y
      - .offset:         184
        .size:           4
        .value_kind:     hidden_block_count_z
      - .offset:         188
        .size:           2
        .value_kind:     hidden_group_size_x
      - .offset:         190
        .size:           2
        .value_kind:     hidden_group_size_y
      - .offset:         192
        .size:           2
        .value_kind:     hidden_group_size_z
      - .offset:         194
        .size:           2
        .value_kind:     hidden_remainder_x
      - .offset:         196
        .size:           2
        .value_kind:     hidden_remainder_y
      - .offset:         198
        .size:           2
        .value_kind:     hidden_remainder_z
      - .offset:         216
        .size:           8
        .value_kind:     hidden_global_offset_x
      - .offset:         224
        .size:           8
        .value_kind:     hidden_global_offset_y
      - .offset:         232
        .size:           8
        .value_kind:     hidden_global_offset_z
      - .offset:         240
        .size:           2
        .value_kind:     hidden_grid_dims
      - .offset:         264
        .size:           8
        .value_kind:     hidden_multigrid_sync_arg
      - .offset:         296
        .size:           4
        .value_kind:     hidden_dynamic_lds_size
    .group_segment_fixed_size: 0
    .kernarg_segment_align: 8
    .kernarg_segment_size: 432
    .language:       OpenCL C
    .language_version:
      - 2
      - 0
    .max_flat_workgroup_size: 512
    .name:           _Z4mega6Paramsii
    .private_segment_fixed_size: 0
    .sgpr_count:     108
    .sgpr_spill_count: 406
    .symbol:         _Z4mega6Paramsii.kd
    .uniform_work_group_size: 1
    .uses_dynamic_stack: false
    .vgpr_count:     252
    .vgpr_spill_count: 0
    .wavefront_size: 64
